# gather expert ranking of heads 1-7: 64-lane DPP bitonic sort + rank push instead of 50x readlane/cmp/addc
# speedup vs baseline: 1.0176x; 1.0090x over previous
.LBB0_328:
	v_ashrrev_i32_e32 v117, 31, v116
	v_lshlrev_b64 v[0:1], 11, v[116:117]
	v_lshl_add_u64 v[134:135], v[122:123], 0, v[0:1]
	global_load_dwordx4 v[12:15], v[134:135], off
	global_load_dwordx4 v[0:3], v[134:135], off offset:16
	v_readlane_b32 s2, v249, 30
	v_readlane_b32 s3, v249, 31
	s_load_dwordx2 s[2:3], s[2:3], 0x180
	v_lshlrev_b64 v[136:137], 10, v[116:117]
	v_mov_b32_e32 v131, v80
	v_mov_b32_e32 v133, v80
	s_movk_i32 s43, 0x80
	s_waitcnt lgkmcnt(0)
	v_lshl_add_u64 v[4:5], s[2:3], 0, v[136:137]
	v_lshl_add_u64 v[18:19], v[4:5], 0, v[130:131]
	v_lshl_add_u64 v[16:17], v[4:5], 0, v[132:133]
	global_load_dword v26, v[16:17], off offset:64
	global_load_dword v28, v[18:19], off
	global_load_dword v25, v[16:17], off offset:192
	global_load_dword v27, v[18:19], off offset:128
	global_load_dwordx4 v[4:7], v[134:135], off offset:48
	global_load_dwordx4 v[8:11], v[134:135], off offset:32
	global_load_dword v21, v[18:19], off offset:256
	global_load_dword v23, v[18:19], off offset:384
	global_load_dword v22, v[18:19], off offset:512
	global_load_dword v24, v[18:19], off offset:640
	global_load_dword v20, v[18:19], off offset:768
	s_nop 0
	global_load_dword v18, v[18:19], off offset:896
	s_nop 0
	global_load_dword v117, v[16:17], off offset:320
	global_load_dword v31, v[16:17], off offset:448
	global_load_dword v30, v[16:17], off offset:576
	global_load_dword v29, v[16:17], off offset:704
	global_load_dword v19, v[16:17], off offset:832
	s_nop 0
	global_load_dword v16, v[16:17], off offset:960
	s_movk_i32 s44, 0x3f80
	v_mov_b32_e32 v176, 0
	v_mov_b32_e32 v177, v176
	v_mov_b32_e32 v216, v176
	v_mov_b32_e32 v217, v176
	v_mov_b32_e32 v214, v176
	v_mov_b32_e32 v215, v176
	v_mov_b32_e32 v212, v176
	v_mov_b32_e32 v213, v176
	v_mov_b32_e32 v210, v176
	v_mov_b32_e32 v211, v176
	v_mov_b32_e32 v208, v176
	v_mov_b32_e32 v209, v176
	v_mov_b32_e32 v206, v176
	v_mov_b32_e32 v207, v176
	v_mov_b32_e32 v204, v176
	v_mov_b32_e32 v205, v176
	v_mov_b32_e32 v202, v176
	v_mov_b32_e32 v203, v176
	v_mov_b32_e32 v200, v176
	v_mov_b32_e32 v201, v176
	v_mov_b32_e32 v198, v176
	v_mov_b32_e32 v199, v176
	v_mov_b32_e32 v196, v176
	v_mov_b32_e32 v197, v176
	v_mov_b32_e32 v194, v176
	v_mov_b32_e32 v195, v176
	v_mov_b32_e32 v192, v176
	v_mov_b32_e32 v193, v176
	v_mov_b32_e32 v190, v176
	v_mov_b32_e32 v191, v176
	v_mov_b32_e32 v188, v176
	v_mov_b32_e32 v189, v176
	s_waitcnt vmcnt(17)
	v_cmp_lt_i32_e32 vcc, -1, v26
	s_waitcnt vmcnt(13)
	v_lshlrev_b32_e32 v160, 16, v4
	v_lshlrev_b32_e32 v152, 16, v12
	v_lshlrev_b32_e32 v174, 16, v1
	v_and_b32_e32 v143, 0xffff0000, v1
	v_cndmask_b32_e64 v1, v232, -1, vcc
	v_cmp_lt_i32_e32 vcc, -1, v28
	v_and_b32_e32 v150, 0xffff0000, v12
	v_lshlrev_b32_e32 v148, 16, v14
	v_cndmask_b32_e64 v12, v232, -1, vcc
	v_cmp_lt_i32_e32 vcc, -1, v25
	v_and_b32_e32 v146, 0xffff0000, v14
	v_lshlrev_b32_e32 v172, 16, v15
	v_cndmask_b32_e64 v17, v232, -1, vcc
	v_cmp_lt_i32_e32 vcc, -1, v27
	v_and_b32_e32 v147, 0xffff0000, v15
	v_lshlrev_b32_e32 v144, 16, v0
	v_and_b32_e32 v142, 0xffff0000, v0
	v_lshlrev_b32_e32 v140, 16, v2
	v_and_b32_e32 v138, 0xffff0000, v2
	v_and_b32_e32 v0, 0xffffff80, v26
	v_and_b32_e32 v2, 0xffffff80, v28
	v_and_b32_e32 v14, 0xffffff80, v25
	v_and_b32_e32 v15, 0xffffff80, v27
	v_cndmask_b32_e64 v32, v232, -1, vcc
	v_lshlrev_b32_e32 v170, 16, v13
	v_and_b32_e32 v151, 0xffff0000, v13
	v_xor_b32_e32 v1, v1, v0
	v_xor_b32_e32 v13, v12, v2
	v_xor_b32_e32 v0, v17, v14
	v_xor_b32_e32 v12, v32, v15
	v_pk_add_f32 v[0:1], v[12:13], v[0:1]
	v_lshlrev_b32_e32 v178, 16, v3
	v_or_b32_e32 v2, 0x80000000, v1
	v_not_b32_e32 v12, v1
	v_cmp_gt_i32_e32 vcc, 0, v1
	v_and_b32_e32 v139, 0xffff0000, v3
	s_waitcnt vmcnt(12)
	v_lshlrev_b32_e32 v168, 16, v8
	v_cndmask_b32_e32 v2, v2, v12, vcc
	v_and_b32_e32 v2, 0xffffffc0, v2
	v_bitop3_b32 v2, v2, 63, v81 bitop3:0x36
	v_cndmask_b32_e64 v2, 0, v2, s[10:11]
	v_and_b32_e32 v166, 0xffff0000, v8
	v_readlane_b32 s3, v2, 1
	v_readlane_b32 s24, v2, 2
	v_readlane_b32 s26, v2, 4
	v_cmp_gt_u32_e32 vcc, s3, v2
	v_readlane_b32 s30, v2, 6
	v_readlane_b32 s34, v2, 8
	v_cndmask_b32_e64 v12, 0, 1, vcc
	v_cmp_gt_u32_e32 vcc, s24, v2
	v_readlane_b32 s2, v2, 0
	v_readlane_b32 s25, v2, 3
	v_cndmask_b32_e64 v13, 0, 1, vcc
	v_cmp_gt_u32_e32 vcc, s26, v2
	v_readlane_b32 s27, v2, 5
	v_readlane_b32 s31, v2, 7
	v_cndmask_b32_e64 v14, 0, 1, vcc
	v_cmp_gt_u32_e32 vcc, s30, v2
	v_and_b32_e32 v158, 0xffff0000, v4
	v_lshlrev_b32_e32 v184, 16, v5
	v_cndmask_b32_e64 v15, 0, 1, vcc
	v_cmp_gt_u32_e32 vcc, s34, v2
	v_and_b32_e32 v159, 0xffff0000, v5
	v_lshlrev_b32_e32 v156, 16, v6
	v_cndmask_b32_e64 v17, 0, 1, vcc
	v_cmp_gt_u32_e32 vcc, s2, v2
	v_readlane_b32 s2, v2, 9
	v_and_b32_e32 v154, 0xffff0000, v6
	v_addc_co_u32_e32 v12, vcc, 0, v12, vcc
	v_cmp_gt_u32_e32 vcc, s25, v2
	v_lshlrev_b32_e32 v5, 7, v28
	v_and_b32_e32 v6, 0x7f, v26
	v_addc_co_u32_e32 v12, vcc, v12, v13, vcc
	v_cmp_gt_u32_e32 vcc, s27, v2
	v_and_or_b32 v5, v5, s44, v6
	v_lshlrev_b32_e32 v186, 16, v7
	v_addc_co_u32_e32 v12, vcc, v12, v14, vcc
	v_cmp_gt_u32_e32 vcc, s31, v2
	v_and_b32_e32 v155, 0xffff0000, v7
	v_lshlrev_b32_e32 v164, 16, v10
	v_addc_co_u32_e32 v12, vcc, v12, v15, vcc
	v_cmp_gt_u32_e32 vcc, s2, v2
	v_readlane_b32 s2, v2, 10
	v_and_b32_e32 v162, 0xffff0000, v10
	v_addc_co_u32_e32 v12, vcc, v12, v17, vcc
	v_cmp_gt_u32_e32 vcc, s2, v2
	v_readlane_b32 s2, v2, 11
	v_lshlrev_b32_e32 v182, 16, v11
	v_cndmask_b32_e64 v13, 0, 1, vcc
	v_cmp_gt_u32_e32 vcc, s2, v2
	v_readlane_b32 s2, v2, 12
	v_and_b32_e32 v163, 0xffff0000, v11
	v_addc_co_u32_e32 v12, vcc, v12, v13, vcc
	v_cmp_gt_u32_e32 vcc, s2, v2
	v_readlane_b32 s2, v2, 13
	v_not_b32_e32 v17, v0
	v_cndmask_b32_e64 v13, 0, 1, vcc
	v_cmp_gt_u32_e32 vcc, s2, v2
	v_readlane_b32 s2, v2, 14
	v_lshlrev_b32_e32 v180, 16, v9
	v_addc_co_u32_e32 v12, vcc, v12, v13, vcc
	v_cmp_gt_u32_e32 vcc, s2, v2
	v_readlane_b32 s2, v2, 15
	v_and_b32_e32 v167, 0xffff0000, v9
	v_cndmask_b32_e64 v13, 0, 1, vcc
	v_cmp_gt_u32_e32 vcc, s2, v2
	v_readlane_b32 s2, v2, 16
	v_and_b32_e32 v9, 0x7f, v25
	v_addc_co_u32_e32 v12, vcc, v12, v13, vcc
	v_cmp_gt_u32_e32 vcc, s2, v2
	v_readlane_b32 s2, v2, 17
	s_mov_b32 s24, 0
	v_cndmask_b32_e64 v13, 0, 1, vcc
	v_cmp_gt_u32_e32 vcc, s2, v2
	v_readlane_b32 s2, v2, 18
	v_mov_b32_e32 v153, v150
	v_addc_co_u32_e32 v12, vcc, v12, v13, vcc
	v_cmp_gt_u32_e32 vcc, s2, v2
	v_readlane_b32 s2, v2, 19
	v_mov_b32_e32 v171, v151
	v_cndmask_b32_e64 v13, 0, 1, vcc
	v_cmp_gt_u32_e32 vcc, s2, v2
	v_readlane_b32 s2, v2, 20
	v_mov_b32_e32 v149, v146
	v_addc_co_u32_e32 v12, vcc, v12, v13, vcc
	v_cmp_gt_u32_e32 vcc, s2, v2
	v_readlane_b32 s2, v2, 21
	v_mov_b32_e32 v173, v147
	v_cndmask_b32_e64 v13, 0, 1, vcc
	v_cmp_gt_u32_e32 vcc, s2, v2
	v_readlane_b32 s2, v2, 22
	v_mov_b32_e32 v145, v142
	v_addc_co_u32_e32 v12, vcc, v12, v13, vcc
	v_cmp_gt_u32_e32 vcc, s2, v2
	v_readlane_b32 s2, v2, 23
	v_mov_b32_e32 v175, v143
	v_cndmask_b32_e64 v13, 0, 1, vcc
	v_cmp_gt_u32_e32 vcc, s2, v2
	v_readlane_b32 s2, v2, 24
	v_mov_b32_e32 v141, v138
	v_addc_co_u32_e32 v12, vcc, v12, v13, vcc
	v_cmp_gt_u32_e32 vcc, s2, v2
	v_readlane_b32 s2, v2, 25
	v_mov_b32_e32 v179, v139
	v_cndmask_b32_e64 v13, 0, 1, vcc
	v_cmp_gt_u32_e32 vcc, s2, v2
	v_readlane_b32 s2, v2, 26
	v_mov_b32_e32 v169, v166
	v_addc_co_u32_e32 v12, vcc, v12, v13, vcc
	v_cmp_gt_u32_e32 vcc, s2, v2
	v_readlane_b32 s2, v2, 27
	v_mov_b32_e32 v181, v167
	v_cndmask_b32_e64 v13, 0, 1, vcc
	v_cmp_gt_u32_e32 vcc, s2, v2
	v_readlane_b32 s2, v2, 28
	v_mov_b32_e32 v165, v162
	v_addc_co_u32_e32 v12, vcc, v12, v13, vcc
	v_cmp_gt_u32_e32 vcc, s2, v2
	v_readlane_b32 s2, v2, 29
	v_mov_b32_e32 v183, v163
	v_cndmask_b32_e64 v13, 0, 1, vcc
	v_cmp_gt_u32_e32 vcc, s2, v2
	v_readlane_b32 s2, v2, 30
	v_mov_b32_e32 v161, v158
	v_addc_co_u32_e32 v12, vcc, v12, v13, vcc
	v_cmp_gt_u32_e32 vcc, s2, v2
	v_readlane_b32 s2, v2, 31
	v_mov_b32_e32 v185, v159
	v_cndmask_b32_e64 v13, 0, 1, vcc
	v_cmp_gt_u32_e32 vcc, s2, v2
	v_readlane_b32 s2, v2, 32
	v_mov_b32_e32 v157, v154
	v_addc_co_u32_e32 v12, vcc, v12, v13, vcc
	v_cmp_gt_u32_e32 vcc, s2, v2
	v_readlane_b32 s2, v2, 33
	v_mov_b32_e32 v187, v155
	v_cndmask_b32_e64 v13, 0, 1, vcc
	v_cmp_gt_u32_e32 vcc, s2, v2
	v_readlane_b32 s2, v2, 34
	s_nop 0
	v_addc_co_u32_e32 v12, vcc, v12, v13, vcc
	v_cmp_gt_u32_e32 vcc, s2, v2
	v_readlane_b32 s2, v2, 35
	s_nop 0
	v_cndmask_b32_e64 v13, 0, 1, vcc
	v_cmp_gt_u32_e32 vcc, s2, v2
	v_readlane_b32 s2, v2, 36
	s_nop 0
	v_addc_co_u32_e32 v12, vcc, v12, v13, vcc
	v_cmp_gt_u32_e32 vcc, s2, v2
	v_readlane_b32 s2, v2, 37
	s_nop 0
	v_cndmask_b32_e64 v13, 0, 1, vcc
	v_cmp_gt_u32_e32 vcc, s2, v2
	v_readlane_b32 s2, v2, 38
	s_nop 0
	v_addc_co_u32_e32 v12, vcc, v12, v13, vcc
	v_cmp_gt_u32_e32 vcc, s2, v2
	v_readlane_b32 s2, v2, 39
	s_nop 0
	v_cndmask_b32_e64 v13, 0, 1, vcc
	v_cmp_gt_u32_e32 vcc, s2, v2
	v_readlane_b32 s2, v2, 40
	s_nop 0
	v_addc_co_u32_e32 v12, vcc, v12, v13, vcc
	v_cmp_gt_u32_e32 vcc, s2, v2
	v_readlane_b32 s2, v2, 41
	s_nop 0
	v_cndmask_b32_e64 v13, 0, 1, vcc
	v_cmp_gt_u32_e32 vcc, s2, v2
	v_readlane_b32 s2, v2, 42
	s_nop 0
	v_addc_co_u32_e32 v12, vcc, v12, v13, vcc
	v_cmp_gt_u32_e32 vcc, s2, v2
	v_readlane_b32 s2, v2, 43
	s_nop 0
	v_cndmask_b32_e64 v13, 0, 1, vcc
	v_cmp_gt_u32_e32 vcc, s2, v2
	v_readlane_b32 s2, v2, 44
	s_nop 0
	v_addc_co_u32_e32 v12, vcc, v12, v13, vcc
	v_cmp_gt_u32_e32 vcc, s2, v2
	v_readlane_b32 s2, v2, 45
	s_nop 0
	v_cndmask_b32_e64 v13, 0, 1, vcc
	v_cmp_gt_u32_e32 vcc, s2, v2
	v_readlane_b32 s2, v2, 46
	s_nop 0
	v_addc_co_u32_e32 v12, vcc, v12, v13, vcc
	v_cmp_gt_u32_e32 vcc, s2, v2
	v_readlane_b32 s2, v2, 47
	s_nop 0
	v_cndmask_b32_e64 v13, 0, 1, vcc
	v_cmp_gt_u32_e32 vcc, s2, v2
	v_readlane_b32 s2, v2, 48
	s_nop 0
	v_addc_co_u32_e32 v12, vcc, v12, v13, vcc
	v_cmp_gt_u32_e32 vcc, s2, v2
	v_readlane_b32 s2, v2, 49
	s_nop 0
	v_cndmask_b32_e64 v13, 0, 1, vcc
	v_cmp_gt_u32_e32 vcc, s2, v2
	s_nop 1
	v_addc_co_u32_e32 v2, vcc, v12, v13, vcc
	v_lshlrev_b32_e32 v13, 3, v2
	v_lshlrev_b32_e32 v12, 7, v2
	v_and_b32_e32 v13, 0x70, v13
	v_and_or_b32 v12, v12, s43, v13
	v_cmp_gt_u32_e32 vcc, 16, v2
	s_nop 1
	v_cndmask_b32_e32 v2, 4, v12, vcc
	ds_permute_b32 v1, v2, v1
	ds_permute_b32 v2, v2, v5
	s_waitcnt lgkmcnt(1)
	v_readlane_b32 s2, v1, 0
	s_nop 1
	v_subrev_f32_e32 v1, s2, v1
	v_mul_f32_e32 v1, 0x3fb8aa3b, v1
	v_exp_f32_e32 v1, v1
	s_waitcnt lgkmcnt(0)
	v_readlane_b32 s25, v2, 4
	v_readlane_b32 s26, v2, 36
	v_readlane_b32 s27, v2, 8
	v_cndmask_b32_e64 v1, 0, v1, s[12:13]
	ds_bpermute_b32 v3, v240, v1
	v_readlane_b32 s30, v2, 40
	v_readlane_b32 s31, v2, 12
	v_readlane_b32 s34, v2, 44
	v_readlane_b32 s35, v2, 16
	s_waitcnt lgkmcnt(0)
	v_add_f32_e32 v3, v1, v3
	ds_bpermute_b32 v8, v241, v3
	v_readlane_b32 s36, v2, 48
	v_readlane_b32 s37, v2, 20
	v_readlane_b32 s38, v2, 52
	v_readlane_b32 s39, v2, 24
	s_waitcnt lgkmcnt(0)
	v_add_f32_e32 v3, v3, v8
	ds_bpermute_b32 v4, v242, v3
	v_readlane_b32 s40, v2, 56
	v_readlane_b32 s41, v2, 28
	v_readlane_b32 s42, v2, 60
	v_lshlrev_b32_e32 v8, 7, v27
	s_waitcnt lgkmcnt(0)
	v_add_f32_e32 v3, v3, v4
	ds_bpermute_b32 v4, v243, v3
	v_and_or_b32 v8, v8, s44, v9
	s_waitcnt lgkmcnt(0)
	v_add_f32_e32 v3, v3, v4
	v_div_scale_f32 v4, s[2:3], v3, v3, v1
	v_rcp_f32_e32 v6, v4
	v_readlane_b32 s2, v2, 0
	v_readlane_b32 s3, v2, 32
	v_fma_f32 v5, -v4, v6, 1.0
	v_fmac_f32_e32 v6, v5, v6
	v_div_scale_f32 v5, vcc, v1, v3, v1
	v_mul_f32_e32 v7, v5, v6
	v_fma_f32 v10, -v4, v7, v5
	v_fmac_f32_e32 v7, v10, v6
	v_fma_f32 v4, -v4, v7, v5
	v_div_fmas_f32 v4, v4, v6, v7
	v_div_fixup_f32 v3, v4, v3, v1
	v_mov_b32_e32 v1, s2
	v_mov_b32_e32 v4, s3
	v_cndmask_b32_e64 v1, v1, v4, s[6:7]
	v_mad_i64_i32 v[4:5], s[2:3], v1, s28, v[118:119]
	global_load_dwordx2 v[36:37], v[4:5], off offset:16
	global_load_dwordx4 v[32:35], v[4:5], off
	v_mov_b32_e32 v4, s25
	v_mov_b32_e32 v5, s26
	v_cndmask_b32_e64 v6, v4, v5, s[6:7]
	v_mad_i64_i32 v[4:5], s[2:3], v6, s28, v[118:119]
	global_load_dwordx2 v[42:43], v[4:5], off offset:16
	global_load_dwordx4 v[38:41], v[4:5], off
	v_mov_b32_e32 v4, s27
	v_mov_b32_e32 v5, s30
	v_cndmask_b32_e64 v10, v4, v5, s[6:7]
	v_mad_i64_i32 v[4:5], s[2:3], v10, s28, v[118:119]
	global_load_dwordx2 v[48:49], v[4:5], off offset:16
	global_load_dwordx4 v[44:47], v[4:5], off
	v_mov_b32_e32 v4, s31
	v_mov_b32_e32 v5, s34
	v_cndmask_b32_e64 v11, v4, v5, s[6:7]
	v_mad_i64_i32 v[4:5], s[2:3], v11, s28, v[118:119]
	global_load_dwordx2 v[54:55], v[4:5], off offset:16
	global_load_dwordx4 v[50:53], v[4:5], off
	v_mov_b32_e32 v4, s35
	v_mov_b32_e32 v5, s36
	v_cndmask_b32_e64 v12, v4, v5, s[6:7]
	v_mad_i64_i32 v[4:5], s[2:3], v12, s28, v[118:119]
	global_load_dwordx2 v[60:61], v[4:5], off offset:16
	global_load_dwordx4 v[56:59], v[4:5], off
	v_mov_b32_e32 v4, s37
	v_mov_b32_e32 v5, s38
	v_cndmask_b32_e64 v13, v4, v5, s[6:7]
	v_mad_i64_i32 v[4:5], s[2:3], v13, s28, v[118:119]
	global_load_dwordx2 v[66:67], v[4:5], off offset:16
	global_load_dwordx4 v[62:65], v[4:5], off
	v_mov_b32_e32 v4, s39
	v_mov_b32_e32 v5, s40
	v_cndmask_b32_e64 v14, v4, v5, s[6:7]
	v_mad_i64_i32 v[4:5], s[2:3], v14, s28, v[118:119]
	global_load_dwordx2 v[72:73], v[4:5], off offset:16
	global_load_dwordx4 v[68:71], v[4:5], off
	v_mov_b32_e32 v4, s41
	v_mov_b32_e32 v5, s42
	v_cndmask_b32_e64 v15, v4, v5, s[6:7]
	v_mad_i64_i32 v[4:5], s[2:3], v15, s28, v[118:119]
	global_load_dwordx2 v[78:79], v[4:5], off offset:16
	global_load_dwordx4 v[74:77], v[4:5], off
	v_mad_i64_i32 v[4:5], s[2:3], v1, s28, v[120:121]
	v_or_b32_e32 v1, 0x80000000, v0
	v_cmp_gt_i32_e32 vcc, 0, v0
	v_mad_i64_i32 v[6:7], s[2:3], v6, s28, v[120:121]
	s_nop 0
	v_cndmask_b32_e32 v1, v1, v17, vcc
	v_and_b32_e32 v1, 0xffffffc0, v1
	v_cndmask_b32_e64 v1, 0, v1, s[10:11]
	v_bitop3_b32 v1, v1, 63, v81 bitop3:0x36
	global_load_dwordx4 v[110:113], v[4:5], off offset:768
	global_load_dwordx4 v[106:109], v[6:7], off offset:768
	s_mov_b32 vcc_lo, 0x55555555
	s_mov_b32 vcc_hi, 0x55555555
	s_mov_b32 s48, 0x33333333
	s_mov_b32 s49, 0x33333333
	v_max_u32_dpp v250, v1, v1 quad_perm:[1,0,3,2] row_mask:0xf bank_mask:0xf
	v_min_u32_dpp v251, v1, v1 quad_perm:[1,0,3,2] row_mask:0xf bank_mask:0xf
	v_cndmask_b32_e32 v17, v251, v250, vcc
	s_nop 1
	v_max_u32_dpp v250, v17, v17 quad_perm:[3,2,1,0] row_mask:0xf bank_mask:0xf
	v_min_u32_dpp v251, v17, v17 quad_perm:[3,2,1,0] row_mask:0xf bank_mask:0xf
	v_cndmask_b32_e64 v1, v251, v250, s[48:49]
	s_nop 1
	v_max_u32_dpp v250, v1, v1 quad_perm:[1,0,3,2] row_mask:0xf bank_mask:0xf
	v_min_u32_dpp v251, v1, v1 quad_perm:[1,0,3,2] row_mask:0xf bank_mask:0xf
	v_cndmask_b32_e32 v17, v251, v250, vcc
	s_nop 1
	v_max_u32_dpp v1, v17, v17 row_half_mirror row_mask:0xf bank_mask:0x5
	v_min_u32_dpp v1, v17, v17 row_half_mirror row_mask:0xf bank_mask:0xa
	s_nop 1
	v_max_u32_dpp v250, v1, v1 quad_perm:[2,3,0,1] row_mask:0xf bank_mask:0xf
	v_min_u32_dpp v251, v1, v1 quad_perm:[2,3,0,1] row_mask:0xf bank_mask:0xf
	v_cndmask_b32_e64 v17, v251, v250, s[48:49]
	s_nop 1
	v_max_u32_dpp v250, v17, v17 quad_perm:[1,0,3,2] row_mask:0xf bank_mask:0xf
	v_min_u32_dpp v251, v17, v17 quad_perm:[1,0,3,2] row_mask:0xf bank_mask:0xf
	v_cndmask_b32_e32 v1, v251, v250, vcc
	s_nop 1
	v_max_u32_dpp v17, v1, v1 row_mirror row_mask:0xf bank_mask:0x3
	v_min_u32_dpp v17, v1, v1 row_mirror row_mask:0xf bank_mask:0xc
	s_nop 1
	v_max_u32_dpp v1, v17, v17 row_ror:12 row_mask:0xf bank_mask:0x5
	v_min_u32_dpp v1, v17, v17 row_ror:4 row_mask:0xf bank_mask:0xa
	s_nop 1
	v_max_u32_dpp v250, v1, v1 quad_perm:[2,3,0,1] row_mask:0xf bank_mask:0xf
	v_min_u32_dpp v251, v1, v1 quad_perm:[2,3,0,1] row_mask:0xf bank_mask:0xf
	v_cndmask_b32_e64 v17, v251, v250, s[48:49]
	s_nop 1
	v_max_u32_dpp v250, v17, v17 quad_perm:[1,0,3,2] row_mask:0xf bank_mask:0xf
	v_min_u32_dpp v251, v17, v17 quad_perm:[1,0,3,2] row_mask:0xf bank_mask:0xf
	v_cndmask_b32_e32 v1, v251, v250, vcc
	ds_swizzle_b32 v252, v1 offset:0x7c1f
	s_waitcnt lgkmcnt(0)
	v_max_u32_dpp v17, v252, v1 quad_perm:[0,1,2,3] row_mask:0x5 bank_mask:0xf
	v_min_u32_dpp v17, v252, v1 quad_perm:[0,1,2,3] row_mask:0xa bank_mask:0xf
	s_nop 1
	v_max_u32_dpp v1, v17, v17 row_ror:8 row_mask:0xf bank_mask:0x3
	v_min_u32_dpp v1, v17, v17 row_ror:8 row_mask:0xf bank_mask:0xc
	s_nop 1
	v_max_u32_dpp v17, v1, v1 row_ror:12 row_mask:0xf bank_mask:0x5
	v_min_u32_dpp v17, v1, v1 row_ror:4 row_mask:0xf bank_mask:0xa
	s_nop 1
	v_max_u32_dpp v250, v17, v17 quad_perm:[2,3,0,1] row_mask:0xf bank_mask:0xf
	v_min_u32_dpp v251, v17, v17 quad_perm:[2,3,0,1] row_mask:0xf bank_mask:0xf
	v_cndmask_b32_e64 v1, v251, v250, s[48:49]
	s_nop 1
	v_max_u32_dpp v250, v1, v1 quad_perm:[1,0,3,2] row_mask:0xf bank_mask:0xf
	v_min_u32_dpp v251, v1, v1 quad_perm:[1,0,3,2] row_mask:0xf bank_mask:0xf
	v_cndmask_b32_e32 v17, v251, v250, vcc
	v_xor_b32_e32 v253, 63, v81
	v_lshlrev_b32_e32 v253, 2, v253
	ds_bpermute_b32 v252, v253, v17
	s_waitcnt lgkmcnt(0)
	v_max_u32_dpp v1, v252, v17 quad_perm:[0,1,2,3] row_mask:0x3 bank_mask:0xf
	v_min_u32_dpp v1, v252, v17 quad_perm:[0,1,2,3] row_mask:0xc bank_mask:0xf
	ds_swizzle_b32 v252, v1 offset:0x401f
	s_waitcnt lgkmcnt(0)
	v_max_u32_dpp v17, v252, v1 quad_perm:[0,1,2,3] row_mask:0x5 bank_mask:0xf
	v_min_u32_dpp v17, v252, v1 quad_perm:[0,1,2,3] row_mask:0xa bank_mask:0xf
	s_nop 1
	v_max_u32_dpp v1, v17, v17 row_ror:8 row_mask:0xf bank_mask:0x3
	v_min_u32_dpp v1, v17, v17 row_ror:8 row_mask:0xf bank_mask:0xc
	s_nop 1
	v_max_u32_dpp v17, v1, v1 row_ror:12 row_mask:0xf bank_mask:0x5
	v_min_u32_dpp v17, v1, v1 row_ror:4 row_mask:0xf bank_mask:0xa
	s_nop 1
	v_max_u32_dpp v250, v17, v17 quad_perm:[2,3,0,1] row_mask:0xf bank_mask:0xf
	v_min_u32_dpp v251, v17, v17 quad_perm:[2,3,0,1] row_mask:0xf bank_mask:0xf
	v_cndmask_b32_e64 v1, v251, v250, s[48:49]
	s_nop 1
	v_max_u32_dpp v250, v1, v1 quad_perm:[1,0,3,2] row_mask:0xf bank_mask:0xf
	v_min_u32_dpp v251, v1, v1 quad_perm:[1,0,3,2] row_mask:0xf bank_mask:0xf
	v_cndmask_b32_e32 v17, v251, v250, vcc
	v_not_b32_e32 v253, v17
	v_and_b32_e32 v253, 63, v253
	v_lshlrev_b32_e32 v253, 2, v253
	ds_permute_b32 v1, v253, v81
	s_waitcnt lgkmcnt(0)
	v_lshlrev_b32_e32 v25, 3, v1
	v_lshlrev_b32_e32 v17, 7, v1
	v_and_b32_e32 v25, 0x70, v25
	v_and_or_b32 v17, v17, s43, v25
	v_cmp_gt_u32_e32 vcc, 16, v1
	s_nop 1
	v_cndmask_b32_e32 v17, 4, v17, vcc
	ds_permute_b32 v25, v17, v0
	v_mad_i64_i32 v[0:1], s[2:3], v10, s28, v[120:121]
	s_waitcnt vmcnt(23)
	v_cmp_lt_i32_e32 vcc, -1, v117
	s_waitcnt lgkmcnt(0)
	v_readlane_b32 s2, v25, 0
	s_nop 1
	v_subrev_f32_e32 v4, s2, v25
	v_mul_f32_e32 v4, 0x3fb8aa3b, v4
	v_exp_f32_e32 v6, v4
	v_mad_i64_i32 v[4:5], s[2:3], v11, s28, v[120:121]
	global_load_dwordx4 v[102:105], v[0:1], off offset:768
	global_load_dwordx4 v[98:101], v[4:5], off offset:768
	v_cndmask_b32_e64 v6, 0, v6, s[12:13]
	ds_bpermute_b32 v7, v240, v6
	v_mad_i64_i32 v[0:1], s[2:3], v12, s28, v[120:121]
	v_mad_i64_i32 v[4:5], s[2:3], v13, s28, v[120:121]
	s_waitcnt lgkmcnt(0)
	v_add_f32_e32 v7, v6, v7
	ds_bpermute_b32 v10, v241, v7
	global_load_dwordx4 v[94:97], v[0:1], off offset:768
	global_load_dwordx4 v[90:93], v[4:5], off offset:768
	v_mad_i64_i32 v[0:1], s[2:3], v14, s28, v[120:121]
	v_mad_i64_i32 v[4:5], s[2:3], v15, s28, v[120:121]
	s_waitcnt lgkmcnt(0)
	v_add_f32_e32 v7, v7, v10
	ds_bpermute_b32 v10, v242, v7
	global_load_dwordx4 v[86:89], v[0:1], off offset:768
	global_load_dwordx4 v[82:85], v[4:5], off offset:768
	v_cndmask_b32_e64 v1, v232, -1, vcc
	v_cmp_lt_i32_e32 vcc, -1, v21
	v_and_b32_e32 v0, 0xffffff80, v117
	s_waitcnt lgkmcnt(0)
	v_add_f32_e32 v7, v7, v10
	v_cndmask_b32_e64 v5, v232, -1, vcc
	s_waitcnt vmcnt(28)
	v_cmp_lt_i32_e32 vcc, -1, v31
	v_and_b32_e32 v4, 0xffffff80, v21
	v_xor_b32_e32 v1, v1, v0
	v_cndmask_b32_e64 v10, v232, -1, vcc
	v_cmp_lt_i32_e32 vcc, -1, v23
	v_xor_b32_e32 v5, v5, v4
	v_and_b32_e32 v0, 0xffffff80, v31
	v_and_b32_e32 v4, 0xffffff80, v23
	v_cndmask_b32_e64 v11, v232, -1, vcc
	v_xor_b32_e32 v0, v10, v0
	v_xor_b32_e32 v4, v11, v4
	v_pk_add_f32 v[0:1], v[4:5], v[0:1]
	ds_bpermute_b32 v9, v243, v7
	v_or_b32_e32 v4, 0x80000000, v1
	v_not_b32_e32 v5, v1
	v_cmp_gt_i32_e32 vcc, 0, v1
	s_nop 1
	v_cndmask_b32_e32 v4, v4, v5, vcc
	v_and_b32_e32 v4, 0xffffffc0, v4
	v_cndmask_b32_e64 v4, 0, v4, s[10:11]
	v_bitop3_b32 v4, v4, 63, v81 bitop3:0x36
	s_nop 0
	s_mov_b32 vcc_lo, 0x55555555
	s_mov_b32 vcc_hi, 0x55555555
	s_mov_b32 s48, 0x33333333
	s_mov_b32 s49, 0x33333333
	v_max_u32_dpp v250, v4, v4 quad_perm:[1,0,3,2] row_mask:0xf bank_mask:0xf
	v_min_u32_dpp v251, v4, v4 quad_perm:[1,0,3,2] row_mask:0xf bank_mask:0xf
	v_cndmask_b32_e32 v5, v251, v250, vcc
	s_nop 1
	v_max_u32_dpp v250, v5, v5 quad_perm:[3,2,1,0] row_mask:0xf bank_mask:0xf
	v_min_u32_dpp v251, v5, v5 quad_perm:[3,2,1,0] row_mask:0xf bank_mask:0xf
	v_cndmask_b32_e64 v4, v251, v250, s[48:49]
	s_nop 1
	v_max_u32_dpp v250, v4, v4 quad_perm:[1,0,3,2] row_mask:0xf bank_mask:0xf
	v_min_u32_dpp v251, v4, v4 quad_perm:[1,0,3,2] row_mask:0xf bank_mask:0xf
	v_cndmask_b32_e32 v5, v251, v250, vcc
	s_nop 1
	v_max_u32_dpp v4, v5, v5 row_half_mirror row_mask:0xf bank_mask:0x5
	v_min_u32_dpp v4, v5, v5 row_half_mirror row_mask:0xf bank_mask:0xa
	s_nop 1
	v_max_u32_dpp v250, v4, v4 quad_perm:[2,3,0,1] row_mask:0xf bank_mask:0xf
	v_min_u32_dpp v251, v4, v4 quad_perm:[2,3,0,1] row_mask:0xf bank_mask:0xf
	v_cndmask_b32_e64 v5, v251, v250, s[48:49]
	s_nop 1
	v_max_u32_dpp v250, v5, v5 quad_perm:[1,0,3,2] row_mask:0xf bank_mask:0xf
	v_min_u32_dpp v251, v5, v5 quad_perm:[1,0,3,2] row_mask:0xf bank_mask:0xf
	v_cndmask_b32_e32 v4, v251, v250, vcc
	s_nop 1
	v_max_u32_dpp v5, v4, v4 row_mirror row_mask:0xf bank_mask:0x3
	v_min_u32_dpp v5, v4, v4 row_mirror row_mask:0xf bank_mask:0xc
	s_nop 1
	v_max_u32_dpp v4, v5, v5 row_ror:12 row_mask:0xf bank_mask:0x5
	v_min_u32_dpp v4, v5, v5 row_ror:4 row_mask:0xf bank_mask:0xa
	s_nop 1
	v_max_u32_dpp v250, v4, v4 quad_perm:[2,3,0,1] row_mask:0xf bank_mask:0xf
	v_min_u32_dpp v251, v4, v4 quad_perm:[2,3,0,1] row_mask:0xf bank_mask:0xf
	v_cndmask_b32_e64 v5, v251, v250, s[48:49]
	s_nop 1
	v_max_u32_dpp v250, v5, v5 quad_perm:[1,0,3,2] row_mask:0xf bank_mask:0xf
	v_min_u32_dpp v251, v5, v5 quad_perm:[1,0,3,2] row_mask:0xf bank_mask:0xf
	v_cndmask_b32_e32 v4, v251, v250, vcc
	ds_swizzle_b32 v252, v4 offset:0x7c1f
	s_waitcnt lgkmcnt(0)
	v_max_u32_dpp v5, v252, v4 quad_perm:[0,1,2,3] row_mask:0x5 bank_mask:0xf
	v_min_u32_dpp v5, v252, v4 quad_perm:[0,1,2,3] row_mask:0xa bank_mask:0xf
	s_nop 1
	v_max_u32_dpp v4, v5, v5 row_ror:8 row_mask:0xf bank_mask:0x3
	v_min_u32_dpp v4, v5, v5 row_ror:8 row_mask:0xf bank_mask:0xc
	s_nop 1
	v_max_u32_dpp v5, v4, v4 row_ror:12 row_mask:0xf bank_mask:0x5
	v_min_u32_dpp v5, v4, v4 row_ror:4 row_mask:0xf bank_mask:0xa
	s_nop 1
	v_max_u32_dpp v250, v5, v5 quad_perm:[2,3,0,1] row_mask:0xf bank_mask:0xf
	v_min_u32_dpp v251, v5, v5 quad_perm:[2,3,0,1] row_mask:0xf bank_mask:0xf
	v_cndmask_b32_e64 v4, v251, v250, s[48:49]
	s_nop 1
	v_max_u32_dpp v250, v4, v4 quad_perm:[1,0,3,2] row_mask:0xf bank_mask:0xf
	v_min_u32_dpp v251, v4, v4 quad_perm:[1,0,3,2] row_mask:0xf bank_mask:0xf
	v_cndmask_b32_e32 v5, v251, v250, vcc
	v_xor_b32_e32 v253, 63, v81
	v_lshlrev_b32_e32 v253, 2, v253
	ds_bpermute_b32 v252, v253, v5
	s_waitcnt lgkmcnt(0)
	v_max_u32_dpp v4, v252, v5 quad_perm:[0,1,2,3] row_mask:0x3 bank_mask:0xf
	v_min_u32_dpp v4, v252, v5 quad_perm:[0,1,2,3] row_mask:0xc bank_mask:0xf
	ds_swizzle_b32 v252, v4 offset:0x401f
	s_waitcnt lgkmcnt(0)
	v_max_u32_dpp v5, v252, v4 quad_perm:[0,1,2,3] row_mask:0x5 bank_mask:0xf
	v_min_u32_dpp v5, v252, v4 quad_perm:[0,1,2,3] row_mask:0xa bank_mask:0xf
	s_nop 1
	v_max_u32_dpp v4, v5, v5 row_ror:8 row_mask:0xf bank_mask:0x3
	v_min_u32_dpp v4, v5, v5 row_ror:8 row_mask:0xf bank_mask:0xc
	s_nop 1
	v_max_u32_dpp v5, v4, v4 row_ror:12 row_mask:0xf bank_mask:0x5
	v_min_u32_dpp v5, v4, v4 row_ror:4 row_mask:0xf bank_mask:0xa
	s_nop 1
	v_max_u32_dpp v250, v5, v5 quad_perm:[2,3,0,1] row_mask:0xf bank_mask:0xf
	v_min_u32_dpp v251, v5, v5 quad_perm:[2,3,0,1] row_mask:0xf bank_mask:0xf
	v_cndmask_b32_e64 v4, v251, v250, s[48:49]
	s_nop 1
	v_max_u32_dpp v250, v4, v4 quad_perm:[1,0,3,2] row_mask:0xf bank_mask:0xf
	v_min_u32_dpp v251, v4, v4 quad_perm:[1,0,3,2] row_mask:0xf bank_mask:0xf
	v_cndmask_b32_e32 v5, v251, v250, vcc
	v_not_b32_e32 v253, v5
	v_and_b32_e32 v253, 63, v253
	v_lshlrev_b32_e32 v253, 2, v253
	ds_permute_b32 v4, v253, v81
	s_waitcnt lgkmcnt(0)
	v_lshlrev_b32_e32 v10, 3, v4
	v_lshlrev_b32_e32 v5, 7, v4
	v_and_b32_e32 v10, 0x70, v10
	v_and_or_b32 v5, v5, s43, v10
	v_cmp_gt_u32_e32 vcc, 16, v4
	ds_permute_b32 v4, v17, v8
	s_nop 0
	v_cndmask_b32_e32 v10, 4, v5, vcc
	ds_permute_b32 v1, v10, v1
	s_waitcnt lgkmcnt(2)
	v_add_f32_e32 v5, v7, v9
	v_div_scale_f32 v7, s[2:3], v5, v5, v6
	v_rcp_f32_e32 v9, v7
	s_waitcnt lgkmcnt(0)
	v_readlane_b32 s2, v1, 0
	v_div_scale_f32 v11, vcc, v6, v5, v6
	s_nop 0
	v_subrev_f32_e32 v1, s2, v1
	v_mul_f32_e32 v1, 0x3fb8aa3b, v1
	v_exp_f32_e32 v1, v1
	v_fma_f32 v8, -v7, v9, 1.0
	v_fmac_f32_e32 v9, v8, v9
	v_mul_f32_e32 v12, v11, v9
	v_cndmask_b32_e64 v1, 0, v1, s[12:13]
	ds_bpermute_b32 v8, v240, v1
	v_fma_f32 v13, -v7, v12, v11
	v_fmac_f32_e32 v12, v13, v9
	v_fma_f32 v7, -v7, v12, v11
	v_div_fmas_f32 v7, v7, v9, v12
	s_waitcnt lgkmcnt(0)
	v_add_f32_e32 v8, v1, v8
	ds_bpermute_b32 v14, v241, v8
	v_div_fixup_f32 v5, v7, v5, v6
	v_or_b32_e32 v6, 0x80000000, v0
	v_not_b32_e32 v7, v0
	v_cmp_gt_i32_e32 vcc, 0, v0
	s_waitcnt lgkmcnt(0)
	v_add_f32_e32 v8, v8, v14
	ds_bpermute_b32 v9, v242, v8
	v_cndmask_b32_e32 v6, v6, v7, vcc
	v_and_b32_e32 v6, 0xffffffc0, v6
	v_cndmask_b32_e64 v6, 0, v6, s[10:11]
	v_bitop3_b32 v6, v6, 63, v81 bitop3:0x36
	ds_write2st64_b64 v239, v[2:3], v[4:5] offset1:1
	s_mov_b32 vcc_lo, 0x55555555
	s_waitcnt lgkmcnt(1)
	v_add_f32_e32 v4, v8, v9
	s_mov_b32 vcc_hi, 0x55555555
	ds_bpermute_b32 v5, v243, v4
	s_mov_b32 s48, 0x33333333
	s_mov_b32 s49, 0x33333333
	v_lshlrev_b32_e32 v2, 7, v21
	v_max_u32_dpp v250, v6, v6 quad_perm:[1,0,3,2] row_mask:0xf bank_mask:0xf
	v_min_u32_dpp v251, v6, v6 quad_perm:[1,0,3,2] row_mask:0xf bank_mask:0xf
	v_cndmask_b32_e32 v7, v251, v250, vcc
	v_and_b32_e32 v3, 0x7f, v117
	s_nop 1
	v_max_u32_dpp v250, v7, v7 quad_perm:[3,2,1,0] row_mask:0xf bank_mask:0xf
	v_min_u32_dpp v251, v7, v7 quad_perm:[3,2,1,0] row_mask:0xf bank_mask:0xf
	v_and_or_b32 v2, v2, s44, v3
	v_cndmask_b32_e64 v6, v251, v250, s[48:49]
	s_nop 1
	v_max_u32_dpp v250, v6, v6 quad_perm:[1,0,3,2] row_mask:0xf bank_mask:0xf
	s_waitcnt lgkmcnt(0)
	v_min_u32_dpp v251, v6, v6 quad_perm:[1,0,3,2] row_mask:0xf bank_mask:0xf
	v_add_f32_e32 v3, v4, v5
	v_cndmask_b32_e32 v7, v251, v250, vcc
	s_nop 1
	v_max_u32_dpp v6, v7, v7 row_half_mirror row_mask:0xf bank_mask:0x5
	ds_permute_b32 v2, v10, v2
	v_min_u32_dpp v6, v7, v7 row_half_mirror row_mask:0xf bank_mask:0xa
	s_nop 1
	v_max_u32_dpp v250, v6, v6 quad_perm:[2,3,0,1] row_mask:0xf bank_mask:0xf
	v_min_u32_dpp v251, v6, v6 quad_perm:[2,3,0,1] row_mask:0xf bank_mask:0xf
	v_cndmask_b32_e64 v7, v251, v250, s[48:49]
	s_nop 1
	v_max_u32_dpp v250, v7, v7 quad_perm:[1,0,3,2] row_mask:0xf bank_mask:0xf
	v_min_u32_dpp v251, v7, v7 quad_perm:[1,0,3,2] row_mask:0xf bank_mask:0xf
	v_cndmask_b32_e32 v6, v251, v250, vcc
	s_nop 1
	v_max_u32_dpp v7, v6, v6 row_mirror row_mask:0xf bank_mask:0x3
	v_min_u32_dpp v7, v6, v6 row_mirror row_mask:0xf bank_mask:0xc
	s_nop 1
	v_max_u32_dpp v6, v7, v7 row_ror:12 row_mask:0xf bank_mask:0x5
	v_min_u32_dpp v6, v7, v7 row_ror:4 row_mask:0xf bank_mask:0xa
	s_nop 1
	v_max_u32_dpp v250, v6, v6 quad_perm:[2,3,0,1] row_mask:0xf bank_mask:0xf
	v_min_u32_dpp v251, v6, v6 quad_perm:[2,3,0,1] row_mask:0xf bank_mask:0xf
	v_cndmask_b32_e64 v7, v251, v250, s[48:49]
	s_nop 1
	v_max_u32_dpp v250, v7, v7 quad_perm:[1,0,3,2] row_mask:0xf bank_mask:0xf
	v_min_u32_dpp v251, v7, v7 quad_perm:[1,0,3,2] row_mask:0xf bank_mask:0xf
	v_cndmask_b32_e32 v6, v251, v250, vcc
	ds_swizzle_b32 v252, v6 offset:0x7c1f
	s_waitcnt lgkmcnt(0)
	v_max_u32_dpp v7, v252, v6 quad_perm:[0,1,2,3] row_mask:0x5 bank_mask:0xf
	v_min_u32_dpp v7, v252, v6 quad_perm:[0,1,2,3] row_mask:0xa bank_mask:0xf
	s_nop 1
	v_max_u32_dpp v6, v7, v7 row_ror:8 row_mask:0xf bank_mask:0x3
	v_min_u32_dpp v6, v7, v7 row_ror:8 row_mask:0xf bank_mask:0xc
	s_nop 1
	v_max_u32_dpp v7, v6, v6 row_ror:12 row_mask:0xf bank_mask:0x5
	v_min_u32_dpp v7, v6, v6 row_ror:4 row_mask:0xf bank_mask:0xa
	s_nop 1
	v_max_u32_dpp v250, v7, v7 quad_perm:[2,3,0,1] row_mask:0xf bank_mask:0xf
	v_min_u32_dpp v251, v7, v7 quad_perm:[2,3,0,1] row_mask:0xf bank_mask:0xf
	v_cndmask_b32_e64 v6, v251, v250, s[48:49]
	s_nop 1
	v_max_u32_dpp v250, v6, v6 quad_perm:[1,0,3,2] row_mask:0xf bank_mask:0xf
	v_min_u32_dpp v251, v6, v6 quad_perm:[1,0,3,2] row_mask:0xf bank_mask:0xf
	v_cndmask_b32_e32 v7, v251, v250, vcc
	v_xor_b32_e32 v253, 63, v81
	v_lshlrev_b32_e32 v253, 2, v253
	ds_bpermute_b32 v252, v253, v7
	s_waitcnt lgkmcnt(0)
	v_max_u32_dpp v6, v252, v7 quad_perm:[0,1,2,3] row_mask:0x3 bank_mask:0xf
	v_min_u32_dpp v6, v252, v7 quad_perm:[0,1,2,3] row_mask:0xc bank_mask:0xf
	ds_swizzle_b32 v252, v6 offset:0x401f
	s_waitcnt lgkmcnt(0)
	v_max_u32_dpp v7, v252, v6 quad_perm:[0,1,2,3] row_mask:0x5 bank_mask:0xf
	v_min_u32_dpp v7, v252, v6 quad_perm:[0,1,2,3] row_mask:0xa bank_mask:0xf
	s_nop 1
	v_max_u32_dpp v6, v7, v7 row_ror:8 row_mask:0xf bank_mask:0x3
	v_min_u32_dpp v6, v7, v7 row_ror:8 row_mask:0xf bank_mask:0xc
	s_nop 1
	v_max_u32_dpp v7, v6, v6 row_ror:12 row_mask:0xf bank_mask:0x5
	v_min_u32_dpp v7, v6, v6 row_ror:4 row_mask:0xf bank_mask:0xa
	s_nop 1
	v_max_u32_dpp v250, v7, v7 quad_perm:[2,3,0,1] row_mask:0xf bank_mask:0xf
	v_min_u32_dpp v251, v7, v7 quad_perm:[2,3,0,1] row_mask:0xf bank_mask:0xf
	v_cndmask_b32_e64 v6, v251, v250, s[48:49]
	s_nop 1
	v_max_u32_dpp v250, v6, v6 quad_perm:[1,0,3,2] row_mask:0xf bank_mask:0xf
	v_min_u32_dpp v251, v6, v6 quad_perm:[1,0,3,2] row_mask:0xf bank_mask:0xf
	v_cndmask_b32_e32 v7, v251, v250, vcc
	v_not_b32_e32 v253, v7
	v_and_b32_e32 v253, 63, v253
	v_lshlrev_b32_e32 v253, 2, v253
	ds_permute_b32 v6, v253, v81
	s_waitcnt lgkmcnt(0)
	v_lshlrev_b32_e32 v8, 3, v6
	v_lshlrev_b32_e32 v7, 7, v6
	v_and_b32_e32 v8, 0x70, v8
	v_and_or_b32 v7, v7, s43, v8
	v_cmp_gt_u32_e32 vcc, 16, v6
	v_and_b32_e32 v8, 0x7f, v31
	s_nop 0
	v_cndmask_b32_e32 v6, 4, v7, vcc
	ds_permute_b32 v0, v6, v0
	v_lshlrev_b32_e32 v7, 7, v23
	v_and_or_b32 v7, v7, s44, v8
	s_waitcnt lgkmcnt(0)
	v_readlane_b32 s2, v0, 0
	s_nop 1
	v_subrev_f32_e32 v0, s2, v0
	v_mul_f32_e32 v0, 0x3fb8aa3b, v0
	v_exp_f32_e32 v0, v0
	v_div_scale_f32 v4, s[2:3], v3, v3, v1
	v_rcp_f32_e32 v5, v4
	v_cndmask_b32_e64 v9, 0, v0, s[12:13]
	ds_bpermute_b32 v0, v240, v9
	v_fma_f32 v10, -v4, v5, 1.0
	v_fmac_f32_e32 v5, v10, v5
	v_div_scale_f32 v10, vcc, v1, v3, v1
	s_waitcnt lgkmcnt(0)
	v_add_f32_e32 v0, v9, v0
	ds_bpermute_b32 v11, v241, v0
	v_mul_f32_e32 v12, v10, v5
	v_fma_f32 v13, -v4, v12, v10
	v_fmac_f32_e32 v12, v13, v5
	v_fma_f32 v4, -v4, v12, v10
	s_waitcnt lgkmcnt(0)
	v_add_f32_e32 v0, v0, v11
	ds_bpermute_b32 v10, v242, v0
	v_div_fmas_f32 v4, v4, v5, v12
	s_waitcnt vmcnt(27)
	v_cmp_lt_i32_e32 vcc, -1, v30
	v_div_fixup_f32 v3, v4, v3, v1
	v_and_b32_e32 v4, 0xffffff80, v22
	v_cndmask_b32_e64 v1, v232, -1, vcc
	v_cmp_lt_i32_e32 vcc, -1, v22
	s_waitcnt lgkmcnt(0)
	v_add_f32_e32 v8, v0, v10
	v_and_b32_e32 v0, 0xffffff80, v30
	v_cndmask_b32_e64 v5, v232, -1, vcc
	s_waitcnt vmcnt(26)
	v_cmp_lt_i32_e32 vcc, -1, v29
	v_xor_b32_e32 v1, v1, v0
	v_xor_b32_e32 v5, v5, v4
	v_cndmask_b32_e64 v11, v232, -1, vcc
	v_cmp_lt_i32_e32 vcc, -1, v24
	v_and_b32_e32 v0, 0xffffff80, v29
	v_and_b32_e32 v4, 0xffffff80, v24
	v_cndmask_b32_e64 v12, v232, -1, vcc
	v_xor_b32_e32 v0, v11, v0
	v_xor_b32_e32 v4, v12, v4
	v_pk_add_f32 v[0:1], v[4:5], v[0:1]
	ds_bpermute_b32 v10, v243, v8
	v_or_b32_e32 v4, 0x80000000, v1
	v_not_b32_e32 v5, v1
	v_cmp_gt_i32_e32 vcc, 0, v1
	s_nop 1
	v_cndmask_b32_e32 v4, v4, v5, vcc
	v_and_b32_e32 v4, 0xffffffc0, v4
	v_cndmask_b32_e64 v4, 0, v4, s[10:11]
	v_bitop3_b32 v4, v4, 63, v81 bitop3:0x36
	s_nop 0
	s_mov_b32 vcc_lo, 0x55555555
	s_mov_b32 vcc_hi, 0x55555555
	s_mov_b32 s48, 0x33333333
	s_mov_b32 s49, 0x33333333
	v_max_u32_dpp v250, v4, v4 quad_perm:[1,0,3,2] row_mask:0xf bank_mask:0xf
	v_min_u32_dpp v251, v4, v4 quad_perm:[1,0,3,2] row_mask:0xf bank_mask:0xf
	v_cndmask_b32_e32 v5, v251, v250, vcc
	s_nop 1
	v_max_u32_dpp v250, v5, v5 quad_perm:[3,2,1,0] row_mask:0xf bank_mask:0xf
	v_min_u32_dpp v251, v5, v5 quad_perm:[3,2,1,0] row_mask:0xf bank_mask:0xf
	v_cndmask_b32_e64 v4, v251, v250, s[48:49]
	s_nop 1
	v_max_u32_dpp v250, v4, v4 quad_perm:[1,0,3,2] row_mask:0xf bank_mask:0xf
	v_min_u32_dpp v251, v4, v4 quad_perm:[1,0,3,2] row_mask:0xf bank_mask:0xf
	v_cndmask_b32_e32 v5, v251, v250, vcc
	s_nop 1
	v_max_u32_dpp v4, v5, v5 row_half_mirror row_mask:0xf bank_mask:0x5
	v_min_u32_dpp v4, v5, v5 row_half_mirror row_mask:0xf bank_mask:0xa
	s_nop 1
	v_max_u32_dpp v250, v4, v4 quad_perm:[2,3,0,1] row_mask:0xf bank_mask:0xf
	v_min_u32_dpp v251, v4, v4 quad_perm:[2,3,0,1] row_mask:0xf bank_mask:0xf
	v_cndmask_b32_e64 v5, v251, v250, s[48:49]
	s_nop 1
	v_max_u32_dpp v250, v5, v5 quad_perm:[1,0,3,2] row_mask:0xf bank_mask:0xf
	v_min_u32_dpp v251, v5, v5 quad_perm:[1,0,3,2] row_mask:0xf bank_mask:0xf
	v_cndmask_b32_e32 v4, v251, v250, vcc
	s_nop 1
	v_max_u32_dpp v5, v4, v4 row_mirror row_mask:0xf bank_mask:0x3
	v_min_u32_dpp v5, v4, v4 row_mirror row_mask:0xf bank_mask:0xc
	s_nop 1
	v_max_u32_dpp v4, v5, v5 row_ror:12 row_mask:0xf bank_mask:0x5
	v_min_u32_dpp v4, v5, v5 row_ror:4 row_mask:0xf bank_mask:0xa
	s_nop 1
	v_max_u32_dpp v250, v4, v4 quad_perm:[2,3,0,1] row_mask:0xf bank_mask:0xf
	v_min_u32_dpp v251, v4, v4 quad_perm:[2,3,0,1] row_mask:0xf bank_mask:0xf
	v_cndmask_b32_e64 v5, v251, v250, s[48:49]
	s_nop 1
	v_max_u32_dpp v250, v5, v5 quad_perm:[1,0,3,2] row_mask:0xf bank_mask:0xf
	v_min_u32_dpp v251, v5, v5 quad_perm:[1,0,3,2] row_mask:0xf bank_mask:0xf
	v_cndmask_b32_e32 v4, v251, v250, vcc
	ds_swizzle_b32 v252, v4 offset:0x7c1f
	s_waitcnt lgkmcnt(0)
	v_max_u32_dpp v5, v252, v4 quad_perm:[0,1,2,3] row_mask:0x5 bank_mask:0xf
	v_min_u32_dpp v5, v252, v4 quad_perm:[0,1,2,3] row_mask:0xa bank_mask:0xf
	s_nop 1
	v_max_u32_dpp v4, v5, v5 row_ror:8 row_mask:0xf bank_mask:0x3
	v_min_u32_dpp v4, v5, v5 row_ror:8 row_mask:0xf bank_mask:0xc
	s_nop 1
	v_max_u32_dpp v5, v4, v4 row_ror:12 row_mask:0xf bank_mask:0x5
	v_min_u32_dpp v5, v4, v4 row_ror:4 row_mask:0xf bank_mask:0xa
	s_nop 1
	v_max_u32_dpp v250, v5, v5 quad_perm:[2,3,0,1] row_mask:0xf bank_mask:0xf
	v_min_u32_dpp v251, v5, v5 quad_perm:[2,3,0,1] row_mask:0xf bank_mask:0xf
	v_cndmask_b32_e64 v4, v251, v250, s[48:49]
	s_nop 1
	v_max_u32_dpp v250, v4, v4 quad_perm:[1,0,3,2] row_mask:0xf bank_mask:0xf
	v_min_u32_dpp v251, v4, v4 quad_perm:[1,0,3,2] row_mask:0xf bank_mask:0xf
	v_cndmask_b32_e32 v5, v251, v250, vcc
	v_xor_b32_e32 v253, 63, v81
	v_lshlrev_b32_e32 v253, 2, v253
	ds_bpermute_b32 v252, v253, v5
	s_waitcnt lgkmcnt(0)
	v_max_u32_dpp v4, v252, v5 quad_perm:[0,1,2,3] row_mask:0x3 bank_mask:0xf
	v_min_u32_dpp v4, v252, v5 quad_perm:[0,1,2,3] row_mask:0xc bank_mask:0xf
	ds_swizzle_b32 v252, v4 offset:0x401f
	s_waitcnt lgkmcnt(0)
	v_max_u32_dpp v5, v252, v4 quad_perm:[0,1,2,3] row_mask:0x5 bank_mask:0xf
	v_min_u32_dpp v5, v252, v4 quad_perm:[0,1,2,3] row_mask:0xa bank_mask:0xf
	s_nop 1
	v_max_u32_dpp v4, v5, v5 row_ror:8 row_mask:0xf bank_mask:0x3
	v_min_u32_dpp v4, v5, v5 row_ror:8 row_mask:0xf bank_mask:0xc
	s_nop 1
	v_max_u32_dpp v5, v4, v4 row_ror:12 row_mask:0xf bank_mask:0x5
	v_min_u32_dpp v5, v4, v4 row_ror:4 row_mask:0xf bank_mask:0xa
	s_nop 1
	v_max_u32_dpp v250, v5, v5 quad_perm:[2,3,0,1] row_mask:0xf bank_mask:0xf
	v_min_u32_dpp v251, v5, v5 quad_perm:[2,3,0,1] row_mask:0xf bank_mask:0xf
	v_cndmask_b32_e64 v4, v251, v250, s[48:49]
	s_nop 1
	v_max_u32_dpp v250, v4, v4 quad_perm:[1,0,3,2] row_mask:0xf bank_mask:0xf
	v_min_u32_dpp v251, v4, v4 quad_perm:[1,0,3,2] row_mask:0xf bank_mask:0xf
	v_cndmask_b32_e32 v5, v251, v250, vcc
	v_not_b32_e32 v253, v5
	v_and_b32_e32 v253, 63, v253
	v_lshlrev_b32_e32 v253, 2, v253
	ds_permute_b32 v4, v253, v81
	s_waitcnt lgkmcnt(0)
	v_lshlrev_b32_e32 v11, 3, v4
	v_lshlrev_b32_e32 v5, 7, v4
	v_and_b32_e32 v11, 0x70, v11
	v_and_or_b32 v5, v5, s43, v11
	v_cmp_gt_u32_e32 vcc, 16, v4
	ds_permute_b32 v4, v6, v7
	s_nop 0
	v_cndmask_b32_e32 v11, 4, v5, vcc
	ds_permute_b32 v1, v11, v1
	s_waitcnt lgkmcnt(2)
	v_add_f32_e32 v5, v8, v10
	v_div_scale_f32 v8, s[2:3], v5, v5, v9
	v_rcp_f32_e32 v10, v8
	s_waitcnt lgkmcnt(0)
	v_readlane_b32 s2, v1, 0
	v_div_scale_f32 v7, vcc, v9, v5, v9
	s_nop 0
	v_subrev_f32_e32 v1, s2, v1
	v_mul_f32_e32 v1, 0x3fb8aa3b, v1
	v_exp_f32_e32 v1, v1
	v_fma_f32 v6, -v8, v10, 1.0
	v_fmac_f32_e32 v10, v6, v10
	v_mul_f32_e32 v12, v7, v10
	v_cndmask_b32_e64 v1, 0, v1, s[12:13]
	ds_bpermute_b32 v6, v240, v1
	v_fma_f32 v13, -v8, v12, v7
	v_fmac_f32_e32 v12, v13, v10
	v_fma_f32 v7, -v8, v12, v7
	v_div_fmas_f32 v7, v7, v10, v12
	s_waitcnt lgkmcnt(0)
	v_add_f32_e32 v6, v1, v6
	ds_bpermute_b32 v14, v241, v6
	v_div_fixup_f32 v5, v7, v5, v9
	ds_write2st64_b64 v239, v[2:3], v[4:5] offset0:2 offset1:3
	v_not_b32_e32 v7, v0
	v_cmp_gt_i32_e32 vcc, 0, v0
	s_waitcnt lgkmcnt(1)
	v_add_f32_e32 v6, v6, v14
	ds_bpermute_b32 v8, v242, v6
	v_lshlrev_b32_e32 v2, 7, v22
	v_and_b32_e32 v3, 0x7f, v30
	v_and_or_b32 v2, v2, s44, v3
	v_lshlrev_b32_e32 v3, 7, v24
	s_waitcnt lgkmcnt(0)
	v_add_f32_e32 v4, v6, v8
	v_or_b32_e32 v6, 0x80000000, v0
	v_cndmask_b32_e32 v6, v6, v7, vcc
	v_and_b32_e32 v6, 0xffffffc0, v6
	v_cndmask_b32_e64 v6, 0, v6, s[10:11]
	v_bitop3_b32 v6, v6, 63, v81 bitop3:0x36
	ds_bpermute_b32 v5, v243, v4
	s_mov_b32 vcc_lo, 0x55555555
	s_waitcnt lgkmcnt(0)
	s_mov_b32 vcc_hi, 0x55555555
	v_add_f32_e32 v4, v4, v5
	s_mov_b32 s48, 0x33333333
	s_mov_b32 s49, 0x33333333
	v_max_u32_dpp v250, v6, v6 quad_perm:[1,0,3,2] row_mask:0xf bank_mask:0xf
	v_min_u32_dpp v251, v6, v6 quad_perm:[1,0,3,2] row_mask:0xf bank_mask:0xf
	v_cndmask_b32_e32 v7, v251, v250, vcc
	s_nop 1
	v_max_u32_dpp v250, v7, v7 quad_perm:[3,2,1,0] row_mask:0xf bank_mask:0xf
	v_min_u32_dpp v251, v7, v7 quad_perm:[3,2,1,0] row_mask:0xf bank_mask:0xf
	v_cndmask_b32_e64 v6, v251, v250, s[48:49]
	s_nop 1
	v_max_u32_dpp v250, v6, v6 quad_perm:[1,0,3,2] row_mask:0xf bank_mask:0xf
	v_min_u32_dpp v251, v6, v6 quad_perm:[1,0,3,2] row_mask:0xf bank_mask:0xf
	v_cndmask_b32_e32 v7, v251, v250, vcc
	s_nop 1
	v_max_u32_dpp v6, v7, v7 row_half_mirror row_mask:0xf bank_mask:0x5
	v_min_u32_dpp v6, v7, v7 row_half_mirror row_mask:0xf bank_mask:0xa
	s_nop 1
	v_max_u32_dpp v250, v6, v6 quad_perm:[2,3,0,1] row_mask:0xf bank_mask:0xf
	v_min_u32_dpp v251, v6, v6 quad_perm:[2,3,0,1] row_mask:0xf bank_mask:0xf
	v_cndmask_b32_e64 v7, v251, v250, s[48:49]
	s_nop 1
	v_max_u32_dpp v250, v7, v7 quad_perm:[1,0,3,2] row_mask:0xf bank_mask:0xf
	v_min_u32_dpp v251, v7, v7 quad_perm:[1,0,3,2] row_mask:0xf bank_mask:0xf
	v_cndmask_b32_e32 v6, v251, v250, vcc
	s_nop 1
	v_max_u32_dpp v7, v6, v6 row_mirror row_mask:0xf bank_mask:0x3
	v_min_u32_dpp v7, v6, v6 row_mirror row_mask:0xf bank_mask:0xc
	s_nop 1
	v_max_u32_dpp v6, v7, v7 row_ror:12 row_mask:0xf bank_mask:0x5
	v_min_u32_dpp v6, v7, v7 row_ror:4 row_mask:0xf bank_mask:0xa
	s_nop 1
	v_max_u32_dpp v250, v6, v6 quad_perm:[2,3,0,1] row_mask:0xf bank_mask:0xf
	v_min_u32_dpp v251, v6, v6 quad_perm:[2,3,0,1] row_mask:0xf bank_mask:0xf
	v_cndmask_b32_e64 v7, v251, v250, s[48:49]
	s_nop 1
	v_max_u32_dpp v250, v7, v7 quad_perm:[1,0,3,2] row_mask:0xf bank_mask:0xf
	v_min_u32_dpp v251, v7, v7 quad_perm:[1,0,3,2] row_mask:0xf bank_mask:0xf
	v_cndmask_b32_e32 v6, v251, v250, vcc
	ds_swizzle_b32 v252, v6 offset:0x7c1f
	s_waitcnt lgkmcnt(0)
	v_max_u32_dpp v7, v252, v6 quad_perm:[0,1,2,3] row_mask:0x5 bank_mask:0xf
	v_min_u32_dpp v7, v252, v6 quad_perm:[0,1,2,3] row_mask:0xa bank_mask:0xf
	s_nop 1
	v_max_u32_dpp v6, v7, v7 row_ror:8 row_mask:0xf bank_mask:0x3
	v_min_u32_dpp v6, v7, v7 row_ror:8 row_mask:0xf bank_mask:0xc
	s_nop 1
	v_max_u32_dpp v7, v6, v6 row_ror:12 row_mask:0xf bank_mask:0x5
	v_min_u32_dpp v7, v6, v6 row_ror:4 row_mask:0xf bank_mask:0xa
	s_nop 1
	v_max_u32_dpp v250, v7, v7 quad_perm:[2,3,0,1] row_mask:0xf bank_mask:0xf
	v_min_u32_dpp v251, v7, v7 quad_perm:[2,3,0,1] row_mask:0xf bank_mask:0xf
	v_cndmask_b32_e64 v6, v251, v250, s[48:49]
	s_nop 1
	v_max_u32_dpp v250, v6, v6 quad_perm:[1,0,3,2] row_mask:0xf bank_mask:0xf
	v_min_u32_dpp v251, v6, v6 quad_perm:[1,0,3,2] row_mask:0xf bank_mask:0xf
	v_cndmask_b32_e32 v7, v251, v250, vcc
	v_xor_b32_e32 v253, 63, v81
	v_lshlrev_b32_e32 v253, 2, v253
	ds_bpermute_b32 v252, v253, v7
	s_waitcnt lgkmcnt(0)
	v_max_u32_dpp v6, v252, v7 quad_perm:[0,1,2,3] row_mask:0x3 bank_mask:0xf
	v_min_u32_dpp v6, v252, v7 quad_perm:[0,1,2,3] row_mask:0xc bank_mask:0xf
	ds_swizzle_b32 v252, v6 offset:0x401f
	s_waitcnt lgkmcnt(0)
	v_max_u32_dpp v7, v252, v6 quad_perm:[0,1,2,3] row_mask:0x5 bank_mask:0xf
	v_min_u32_dpp v7, v252, v6 quad_perm:[0,1,2,3] row_mask:0xa bank_mask:0xf
	s_nop 1
	v_max_u32_dpp v6, v7, v7 row_ror:8 row_mask:0xf bank_mask:0x3
	v_min_u32_dpp v6, v7, v7 row_ror:8 row_mask:0xf bank_mask:0xc
	s_nop 1
	v_max_u32_dpp v7, v6, v6 row_ror:12 row_mask:0xf bank_mask:0x5
	v_min_u32_dpp v7, v6, v6 row_ror:4 row_mask:0xf bank_mask:0xa
	s_nop 1
	v_max_u32_dpp v250, v7, v7 quad_perm:[2,3,0,1] row_mask:0xf bank_mask:0xf
	v_min_u32_dpp v251, v7, v7 quad_perm:[2,3,0,1] row_mask:0xf bank_mask:0xf
	v_cndmask_b32_e64 v6, v251, v250, s[48:49]
	s_nop 1
	v_max_u32_dpp v250, v6, v6 quad_perm:[1,0,3,2] row_mask:0xf bank_mask:0xf
	v_min_u32_dpp v251, v6, v6 quad_perm:[1,0,3,2] row_mask:0xf bank_mask:0xf
	v_cndmask_b32_e32 v7, v251, v250, vcc
	v_not_b32_e32 v253, v7
	v_and_b32_e32 v253, 63, v253
	v_lshlrev_b32_e32 v253, 2, v253
	ds_permute_b32 v6, v253, v81
	s_waitcnt lgkmcnt(0)
	v_lshlrev_b32_e32 v8, 3, v6
	v_lshlrev_b32_e32 v7, 7, v6
	v_and_b32_e32 v8, 0x70, v8
	v_and_or_b32 v7, v7, s43, v8
	v_cmp_gt_u32_e32 vcc, 16, v6
	s_nop 1
	v_cndmask_b32_e32 v6, 4, v7, vcc
	ds_permute_b32 v0, v6, v0
	v_and_b32_e32 v7, 0x7f, v29
	v_and_or_b32 v7, v3, s44, v7
	s_waitcnt lgkmcnt(0)
	v_readlane_b32 s2, v0, 0
	s_nop 1
	v_subrev_f32_e32 v0, s2, v0
	v_mul_f32_e32 v0, 0x3fb8aa3b, v0
	v_exp_f32_e32 v5, v0
	ds_permute_b32 v0, v11, v2
	v_div_scale_f32 v8, s[2:3], v4, v4, v1
	v_cndmask_b32_e64 v10, 0, v5, s[12:13]
	ds_bpermute_b32 v2, v240, v10
	v_rcp_f32_e32 v9, v8
	s_waitcnt lgkmcnt(0)
	v_add_f32_e32 v2, v10, v2
	ds_bpermute_b32 v11, v241, v2
	v_fma_f32 v5, -v8, v9, 1.0
	v_fmac_f32_e32 v9, v5, v9
	v_div_scale_f32 v5, vcc, v1, v4, v1
	v_mul_f32_e32 v12, v5, v9
	v_fma_f32 v13, -v8, v12, v5
	v_fmac_f32_e32 v12, v13, v9
	s_waitcnt lgkmcnt(0)
	v_add_f32_e32 v2, v2, v11
	v_fma_f32 v5, -v8, v12, v5
	ds_bpermute_b32 v8, v242, v2
	v_div_fmas_f32 v5, v5, v9, v12
	s_waitcnt vmcnt(25)
	v_cmp_lt_i32_e32 vcc, -1, v19
	v_div_fixup_f32 v1, v5, v4, v1
	v_and_b32_e32 v4, 0xffffff80, v20
	v_cndmask_b32_e64 v3, v232, -1, vcc
	v_cmp_lt_i32_e32 vcc, -1, v20
	s_waitcnt lgkmcnt(0)
	v_add_f32_e32 v8, v2, v8
	v_and_b32_e32 v2, 0xffffff80, v19
	v_cndmask_b32_e64 v5, v232, -1, vcc
	s_waitcnt vmcnt(24)
	v_cmp_lt_i32_e32 vcc, -1, v16
	v_xor_b32_e32 v3, v3, v2
	v_xor_b32_e32 v5, v5, v4
	v_cndmask_b32_e64 v11, v232, -1, vcc
	v_cmp_lt_i32_e32 vcc, -1, v18
	v_and_b32_e32 v2, 0xffffff80, v16
	v_and_b32_e32 v4, 0xffffff80, v18
	v_cndmask_b32_e64 v12, v232, -1, vcc
	v_xor_b32_e32 v2, v11, v2
	v_xor_b32_e32 v4, v12, v4
	v_pk_add_f32 v[2:3], v[4:5], v[2:3]
	ds_bpermute_b32 v9, v243, v8
	v_or_b32_e32 v4, 0x80000000, v3
	v_not_b32_e32 v5, v3
	v_cmp_gt_i32_e32 vcc, 0, v3
	s_nop 1
	v_cndmask_b32_e32 v4, v4, v5, vcc
	v_and_b32_e32 v4, 0xffffffc0, v4
	v_cndmask_b32_e64 v4, 0, v4, s[10:11]
	v_bitop3_b32 v4, v4, 63, v81 bitop3:0x36
	s_nop 0
	s_mov_b32 vcc_lo, 0x55555555
	s_mov_b32 vcc_hi, 0x55555555
	s_mov_b32 s48, 0x33333333
	s_mov_b32 s49, 0x33333333
	v_max_u32_dpp v250, v4, v4 quad_perm:[1,0,3,2] row_mask:0xf bank_mask:0xf
	v_min_u32_dpp v251, v4, v4 quad_perm:[1,0,3,2] row_mask:0xf bank_mask:0xf
	v_cndmask_b32_e32 v5, v251, v250, vcc
	s_nop 1
	v_max_u32_dpp v250, v5, v5 quad_perm:[3,2,1,0] row_mask:0xf bank_mask:0xf
	v_min_u32_dpp v251, v5, v5 quad_perm:[3,2,1,0] row_mask:0xf bank_mask:0xf
	v_cndmask_b32_e64 v4, v251, v250, s[48:49]
	s_nop 1
	v_max_u32_dpp v250, v4, v4 quad_perm:[1,0,3,2] row_mask:0xf bank_mask:0xf
	v_min_u32_dpp v251, v4, v4 quad_perm:[1,0,3,2] row_mask:0xf bank_mask:0xf
	v_cndmask_b32_e32 v5, v251, v250, vcc
	s_nop 1
	v_max_u32_dpp v4, v5, v5 row_half_mirror row_mask:0xf bank_mask:0x5
	v_min_u32_dpp v4, v5, v5 row_half_mirror row_mask:0xf bank_mask:0xa
	s_nop 1
	v_max_u32_dpp v250, v4, v4 quad_perm:[2,3,0,1] row_mask:0xf bank_mask:0xf
	v_min_u32_dpp v251, v4, v4 quad_perm:[2,3,0,1] row_mask:0xf bank_mask:0xf
	v_cndmask_b32_e64 v5, v251, v250, s[48:49]
	s_nop 1
	v_max_u32_dpp v250, v5, v5 quad_perm:[1,0,3,2] row_mask:0xf bank_mask:0xf
	v_min_u32_dpp v251, v5, v5 quad_perm:[1,0,3,2] row_mask:0xf bank_mask:0xf
	v_cndmask_b32_e32 v4, v251, v250, vcc
	s_nop 1
	v_max_u32_dpp v5, v4, v4 row_mirror row_mask:0xf bank_mask:0x3
	v_min_u32_dpp v5, v4, v4 row_mirror row_mask:0xf bank_mask:0xc
	s_nop 1
	v_max_u32_dpp v4, v5, v5 row_ror:12 row_mask:0xf bank_mask:0x5
	v_min_u32_dpp v4, v5, v5 row_ror:4 row_mask:0xf bank_mask:0xa
	s_nop 1
	v_max_u32_dpp v250, v4, v4 quad_perm:[2,3,0,1] row_mask:0xf bank_mask:0xf
	v_min_u32_dpp v251, v4, v4 quad_perm:[2,3,0,1] row_mask:0xf bank_mask:0xf
	v_cndmask_b32_e64 v5, v251, v250, s[48:49]
	s_nop 1
	v_max_u32_dpp v250, v5, v5 quad_perm:[1,0,3,2] row_mask:0xf bank_mask:0xf
	v_min_u32_dpp v251, v5, v5 quad_perm:[1,0,3,2] row_mask:0xf bank_mask:0xf
	v_cndmask_b32_e32 v4, v251, v250, vcc
	ds_swizzle_b32 v252, v4 offset:0x7c1f
	s_waitcnt lgkmcnt(0)
	v_max_u32_dpp v5, v252, v4 quad_perm:[0,1,2,3] row_mask:0x5 bank_mask:0xf
	v_min_u32_dpp v5, v252, v4 quad_perm:[0,1,2,3] row_mask:0xa bank_mask:0xf
	s_nop 1
	v_max_u32_dpp v4, v5, v5 row_ror:8 row_mask:0xf bank_mask:0x3
	v_min_u32_dpp v4, v5, v5 row_ror:8 row_mask:0xf bank_mask:0xc
	s_nop 1
	v_max_u32_dpp v5, v4, v4 row_ror:12 row_mask:0xf bank_mask:0x5
	v_min_u32_dpp v5, v4, v4 row_ror:4 row_mask:0xf bank_mask:0xa
	s_nop 1
	v_max_u32_dpp v250, v5, v5 quad_perm:[2,3,0,1] row_mask:0xf bank_mask:0xf
	v_min_u32_dpp v251, v5, v5 quad_perm:[2,3,0,1] row_mask:0xf bank_mask:0xf
	v_cndmask_b32_e64 v4, v251, v250, s[48:49]
	s_nop 1
	v_max_u32_dpp v250, v4, v4 quad_perm:[1,0,3,2] row_mask:0xf bank_mask:0xf
	v_min_u32_dpp v251, v4, v4 quad_perm:[1,0,3,2] row_mask:0xf bank_mask:0xf
	v_cndmask_b32_e32 v5, v251, v250, vcc
	v_xor_b32_e32 v253, 63, v81
	v_lshlrev_b32_e32 v253, 2, v253
	ds_bpermute_b32 v252, v253, v5
	s_waitcnt lgkmcnt(0)
	v_max_u32_dpp v4, v252, v5 quad_perm:[0,1,2,3] row_mask:0x3 bank_mask:0xf
	v_min_u32_dpp v4, v252, v5 quad_perm:[0,1,2,3] row_mask:0xc bank_mask:0xf
	ds_swizzle_b32 v252, v4 offset:0x401f
	s_waitcnt lgkmcnt(0)
	v_max_u32_dpp v5, v252, v4 quad_perm:[0,1,2,3] row_mask:0x5 bank_mask:0xf
	v_min_u32_dpp v5, v252, v4 quad_perm:[0,1,2,3] row_mask:0xa bank_mask:0xf
	s_nop 1
	v_max_u32_dpp v4, v5, v5 row_ror:8 row_mask:0xf bank_mask:0x3
	v_min_u32_dpp v4, v5, v5 row_ror:8 row_mask:0xf bank_mask:0xc
	s_nop 1
	v_max_u32_dpp v5, v4, v4 row_ror:12 row_mask:0xf bank_mask:0x5
	v_min_u32_dpp v5, v4, v4 row_ror:4 row_mask:0xf bank_mask:0xa
	s_nop 1
	v_max_u32_dpp v250, v5, v5 quad_perm:[2,3,0,1] row_mask:0xf bank_mask:0xf
	v_min_u32_dpp v251, v5, v5 quad_perm:[2,3,0,1] row_mask:0xf bank_mask:0xf
	v_cndmask_b32_e64 v4, v251, v250, s[48:49]
	s_nop 1
	v_max_u32_dpp v250, v4, v4 quad_perm:[1,0,3,2] row_mask:0xf bank_mask:0xf
	v_min_u32_dpp v251, v4, v4 quad_perm:[1,0,3,2] row_mask:0xf bank_mask:0xf
	v_cndmask_b32_e32 v5, v251, v250, vcc
	v_not_b32_e32 v253, v5
	v_and_b32_e32 v253, 63, v253
	v_lshlrev_b32_e32 v253, 2, v253
	ds_permute_b32 v4, v253, v81
	s_waitcnt lgkmcnt(0)
	v_lshlrev_b32_e32 v11, 3, v4
	v_lshlrev_b32_e32 v5, 7, v4
	v_and_b32_e32 v11, 0x70, v11
	v_and_or_b32 v5, v5, s43, v11
	v_cmp_gt_u32_e32 vcc, 16, v4
	ds_permute_b32 v4, v6, v7
	s_nop 0
	v_cndmask_b32_e32 v11, 4, v5, vcc
	s_waitcnt lgkmcnt(1)
	v_add_f32_e32 v5, v8, v9
	v_div_scale_f32 v8, s[2:3], v5, v5, v10
	v_rcp_f32_e32 v9, v8
	v_div_scale_f32 v7, vcc, v10, v5, v10
	ds_permute_b32 v3, v11, v3
	v_fma_f32 v6, -v8, v9, 1.0
	v_fmac_f32_e32 v9, v6, v9
	v_mul_f32_e32 v12, v7, v9
	v_fma_f32 v13, -v8, v12, v7
	v_fmac_f32_e32 v12, v13, v9
	v_fma_f32 v7, -v8, v12, v7
	v_div_fmas_f32 v7, v7, v9, v12
	v_or_b32_e32 v8, 0x80000000, v2
	v_not_b32_e32 v9, v2
	v_cmp_gt_i32_e32 vcc, 0, v2
	s_waitcnt lgkmcnt(0)
	v_readlane_b32 s2, v3, 0
	v_div_fixup_f32 v5, v7, v5, v10
	v_cndmask_b32_e32 v8, v8, v9, vcc
	v_and_b32_e32 v8, 0xffffffc0, v8
	v_cndmask_b32_e64 v8, 0, v8, s[10:11]
	v_bitop3_b32 v8, v8, 63, v81 bitop3:0x36
	v_subrev_f32_e32 v3, s2, v3
	s_mov_b32 vcc_lo, 0x55555555
	v_mul_f32_e32 v3, 0x3fb8aa3b, v3
	v_exp_f32_e32 v3, v3
	s_mov_b32 vcc_hi, 0x55555555
	s_mov_b32 s48, 0x33333333
	s_mov_b32 s49, 0x33333333
	ds_write2st64_b64 v239, v[0:1], v[4:5] offset0:4 offset1:5
	v_max_u32_dpp v250, v8, v8 quad_perm:[1,0,3,2] row_mask:0xf bank_mask:0xf
	v_min_u32_dpp v251, v8, v8 quad_perm:[1,0,3,2] row_mask:0xf bank_mask:0xf
	v_cndmask_b32_e32 v9, v251, v250, vcc
	v_cndmask_b32_e64 v3, 0, v3, s[12:13]
	s_nop 1
	v_max_u32_dpp v250, v9, v9 quad_perm:[3,2,1,0] row_mask:0xf bank_mask:0xf
	v_min_u32_dpp v251, v9, v9 quad_perm:[3,2,1,0] row_mask:0xf bank_mask:0xf
	ds_bpermute_b32 v6, v240, v3
	v_cndmask_b32_e64 v8, v251, v250, s[48:49]
	s_nop 1
	v_max_u32_dpp v250, v8, v8 quad_perm:[1,0,3,2] row_mask:0xf bank_mask:0xf
	v_lshlrev_b32_e32 v0, 7, v20
	v_min_u32_dpp v251, v8, v8 quad_perm:[1,0,3,2] row_mask:0xf bank_mask:0xf
	v_cndmask_b32_e32 v9, v251, v250, vcc
	s_nop 1
	s_waitcnt lgkmcnt(0)
	v_add_f32_e32 v6, v3, v6
	v_max_u32_dpp v8, v9, v9 row_half_mirror row_mask:0xf bank_mask:0x5
	v_min_u32_dpp v8, v9, v9 row_half_mirror row_mask:0xf bank_mask:0xa
	s_nop 1
	ds_bpermute_b32 v13, v241, v6
	v_max_u32_dpp v250, v8, v8 quad_perm:[2,3,0,1] row_mask:0xf bank_mask:0xf
	v_min_u32_dpp v251, v8, v8 quad_perm:[2,3,0,1] row_mask:0xf bank_mask:0xf
	v_cndmask_b32_e64 v9, v251, v250, s[48:49]
	s_waitcnt lgkmcnt(0)
	s_nop 1
	v_add_f32_e32 v6, v6, v13
	v_max_u32_dpp v250, v9, v9 quad_perm:[1,0,3,2] row_mask:0xf bank_mask:0xf
	v_min_u32_dpp v251, v9, v9 quad_perm:[1,0,3,2] row_mask:0xf bank_mask:0xf
	v_cndmask_b32_e32 v8, v251, v250, vcc
	ds_bpermute_b32 v7, v242, v6
	s_nop 1
	v_max_u32_dpp v9, v8, v8 row_mirror row_mask:0xf bank_mask:0x3
	v_min_u32_dpp v9, v8, v8 row_mirror row_mask:0xf bank_mask:0xc
	v_and_b32_e32 v1, 0x7f, v19
	s_nop 1
	v_max_u32_dpp v8, v9, v9 row_ror:12 row_mask:0xf bank_mask:0x5
	v_min_u32_dpp v8, v9, v9 row_ror:4 row_mask:0xf bank_mask:0xa
	s_waitcnt lgkmcnt(0)
	s_nop 1
	v_add_f32_e32 v4, v6, v7
	v_max_u32_dpp v250, v8, v8 quad_perm:[2,3,0,1] row_mask:0xf bank_mask:0xf
	v_min_u32_dpp v251, v8, v8 quad_perm:[2,3,0,1] row_mask:0xf bank_mask:0xf
	v_cndmask_b32_e64 v9, v251, v250, s[48:49]
	v_and_or_b32 v0, v0, s44, v1
	s_nop 1
	v_max_u32_dpp v250, v9, v9 quad_perm:[1,0,3,2] row_mask:0xf bank_mask:0xf
	v_min_u32_dpp v251, v9, v9 quad_perm:[1,0,3,2] row_mask:0xf bank_mask:0xf
	ds_bpermute_b32 v5, v243, v4
	v_cndmask_b32_e32 v8, v251, v250, vcc
	ds_swizzle_b32 v252, v8 offset:0x7c1f
	s_waitcnt lgkmcnt(0)
	ds_permute_b32 v0, v11, v0
	v_max_u32_dpp v9, v252, v8 quad_perm:[0,1,2,3] row_mask:0x5 bank_mask:0xf
	v_min_u32_dpp v9, v252, v8 quad_perm:[0,1,2,3] row_mask:0xa bank_mask:0xf
	v_lshlrev_b32_e32 v6, 7, v18
	s_nop 1
	v_max_u32_dpp v8, v9, v9 row_ror:8 row_mask:0xf bank_mask:0x3
	v_min_u32_dpp v8, v9, v9 row_ror:8 row_mask:0xf bank_mask:0xc
	s_nop 1
	v_max_u32_dpp v9, v8, v8 row_ror:12 row_mask:0xf bank_mask:0x5
	v_min_u32_dpp v9, v8, v8 row_ror:4 row_mask:0xf bank_mask:0xa
	s_nop 1
	v_max_u32_dpp v250, v9, v9 quad_perm:[2,3,0,1] row_mask:0xf bank_mask:0xf
	v_min_u32_dpp v251, v9, v9 quad_perm:[2,3,0,1] row_mask:0xf bank_mask:0xf
	v_cndmask_b32_e64 v8, v251, v250, s[48:49]
	s_nop 1
	v_max_u32_dpp v250, v8, v8 quad_perm:[1,0,3,2] row_mask:0xf bank_mask:0xf
	v_min_u32_dpp v251, v8, v8 quad_perm:[1,0,3,2] row_mask:0xf bank_mask:0xf
	v_cndmask_b32_e32 v9, v251, v250, vcc
	v_xor_b32_e32 v253, 63, v81
	v_lshlrev_b32_e32 v253, 2, v253
	ds_bpermute_b32 v252, v253, v9
	s_waitcnt lgkmcnt(0)
	v_max_u32_dpp v8, v252, v9 quad_perm:[0,1,2,3] row_mask:0x3 bank_mask:0xf
	v_min_u32_dpp v8, v252, v9 quad_perm:[0,1,2,3] row_mask:0xc bank_mask:0xf
	ds_swizzle_b32 v252, v8 offset:0x401f
	s_waitcnt lgkmcnt(0)
	v_max_u32_dpp v9, v252, v8 quad_perm:[0,1,2,3] row_mask:0x5 bank_mask:0xf
	v_min_u32_dpp v9, v252, v8 quad_perm:[0,1,2,3] row_mask:0xa bank_mask:0xf
	s_nop 1
	v_max_u32_dpp v8, v9, v9 row_ror:8 row_mask:0xf bank_mask:0x3
	v_min_u32_dpp v8, v9, v9 row_ror:8 row_mask:0xf bank_mask:0xc
	s_nop 1
	v_max_u32_dpp v9, v8, v8 row_ror:12 row_mask:0xf bank_mask:0x5
	v_min_u32_dpp v9, v8, v8 row_ror:4 row_mask:0xf bank_mask:0xa
	s_nop 1
	v_max_u32_dpp v250, v9, v9 quad_perm:[2,3,0,1] row_mask:0xf bank_mask:0xf
	v_min_u32_dpp v251, v9, v9 quad_perm:[2,3,0,1] row_mask:0xf bank_mask:0xf
	v_cndmask_b32_e64 v8, v251, v250, s[48:49]
	s_nop 1
	v_max_u32_dpp v250, v8, v8 quad_perm:[1,0,3,2] row_mask:0xf bank_mask:0xf
	v_min_u32_dpp v251, v8, v8 quad_perm:[1,0,3,2] row_mask:0xf bank_mask:0xf
	v_cndmask_b32_e32 v9, v251, v250, vcc
	v_not_b32_e32 v253, v9
	v_and_b32_e32 v253, 63, v253
	v_lshlrev_b32_e32 v253, 2, v253
	ds_permute_b32 v8, v253, v81
	s_waitcnt lgkmcnt(0)
	v_lshlrev_b32_e32 v10, 3, v8
	v_lshlrev_b32_e32 v9, 7, v8
	v_and_b32_e32 v10, 0x70, v10
	v_and_or_b32 v9, v9, s43, v10
	v_cmp_gt_u32_e32 vcc, 16, v8
	v_and_b32_e32 v10, 0x7f, v16
	s_nop 0
	v_cndmask_b32_e32 v8, 4, v9, vcc
	ds_permute_b32 v2, v8, v2
	s_waitcnt lgkmcnt(0)
	v_readlane_b32 s2, v2, 0
	s_nop 1
	v_subrev_f32_e32 v2, s2, v2
	v_mul_f32_e32 v2, 0x3fb8aa3b, v2
	v_exp_f32_e32 v2, v2
	s_nop 0
	v_cndmask_b32_e64 v7, 0, v2, s[12:13]
	ds_bpermute_b32 v1, v240, v7
	v_add_f32_e32 v2, v4, v5
	v_div_scale_f32 v4, s[2:3], v2, v2, v3
	v_rcp_f32_e32 v5, v4
	s_waitcnt lgkmcnt(0)
	v_add_f32_e32 v1, v7, v1
	ds_bpermute_b32 v9, v241, v1
	v_fma_f32 v11, -v4, v5, 1.0
	v_fmac_f32_e32 v5, v11, v5
	v_div_scale_f32 v11, vcc, v3, v2, v3
	s_waitcnt lgkmcnt(0)
	v_add_f32_e32 v1, v1, v9
	ds_bpermute_b32 v9, v242, v1
	v_mul_f32_e32 v12, v11, v5
	v_fma_f32 v13, -v4, v12, v11
	v_fmac_f32_e32 v12, v13, v5
	v_fma_f32 v4, -v4, v12, v11
	s_waitcnt lgkmcnt(0)
	v_add_f32_e32 v1, v1, v9
	ds_bpermute_b32 v9, v243, v1
	v_div_fmas_f32 v4, v4, v5, v12
	s_waitcnt lgkmcnt(0)
	v_add_f32_e32 v5, v1, v9
	v_div_scale_f32 v9, s[2:3], v5, v5, v7
	v_rcp_f32_e32 v11, v9
	v_div_fixup_f32 v1, v4, v2, v3
	v_and_or_b32 v2, v6, s44, v10
	ds_permute_b32 v2, v8, v2
	v_fma_f32 v3, -v9, v11, 1.0
	v_fmac_f32_e32 v11, v3, v11
	v_div_scale_f32 v3, vcc, v7, v5, v7
	v_mul_f32_e32 v4, v3, v11
	v_fma_f32 v6, -v9, v4, v3
	v_fmac_f32_e32 v4, v6, v11
	v_fma_f32 v3, -v9, v4, v3
	v_div_fmas_f32 v3, v3, v11, v4
	v_div_fixup_f32 v3, v3, v5, v7
	s_waitcnt lgkmcnt(0)
	ds_write2st64_b64 v239, v[0:1], v[2:3] offset0:6 offset1:7
	s_branch .LBB0_330
